# speedup vs baseline: 1.0027x; 1.0027x over previous
; __device__ __forceinline__ unsigned xb_ld(unsigned* p)              { return __hip_atomic_load(p, __ATOMIC_RELAXED, __HIP_MEMORY_SCOPE_AGENT); }
; __device__ __forceinline__ void xcd_barrier_complete(unsigned* bar, unsigned x, unsigned& nloc, unsigned& nx) {
;     const unsigned G = gridDim.x * gridDim.y * gridDim.z;
;     unsigned sum, cnt, mine, sp = 0u;
;     for (;;) {
;         sum = 0u; cnt = 0u; mine = 0u;
; #pragma unroll
;         for (unsigned j = 0; j < 16; ++j) { const unsigned c = xb_ld(&bar[XB_XCNT(j)]); sum += c; cnt += (c > 0u) ? 1u : 0u; mine = (j == x) ? c : mine; }
;         if (sum == G) break;
;         __builtin_amdgcn_s_sleep(1);
;         if ((++sp & 255u) == 0u) { if (xb_ld(&bar[XB_TMO])) break; if (sp > XB_SPIN_CAP) { atomicAdd(&bar[XB_TMO], 1u); break; } }
;     }
.LBB0_453:
	v_readlane_b32 s10, v249, 42
	v_readlane_b32 s11, v249, 43
	v_readlane_b32 s5, v247, 49
	s_mov_b64 s[12:13], -1
	s_nop 2
	global_load_dword v0, v1, s[10:11] sc1
	v_readlane_b32 s10, v249, 44
	v_readlane_b32 s11, v249, 45
	s_waitcnt lgkmcnt(0)
	s_nop 3
	global_load_dword v2, v1, s[10:11] sc1
	v_readlane_b32 s10, v249, 46
	v_readlane_b32 s11, v249, 47
	s_nop 0
	s_nop 0
	s_nop 2
	global_load_dword v3, v1, s[10:11] sc1
	v_readlane_b32 s10, v249, 48
	v_readlane_b32 s11, v249, 49
	s_nop 0
	s_nop 0
	s_nop 2
	global_load_dword v4, v1, s[10:11] sc1
	v_readlane_b32 s10, v249, 50
	v_readlane_b32 s11, v249, 51
	s_nop 0
	s_nop 0
	s_nop 2
	global_load_dword v5, v1, s[10:11] sc1
	v_readlane_b32 s10, v249, 52
	v_readlane_b32 s11, v249, 53
	s_nop 0
	s_nop 0
	s_nop 2
	global_load_dword v6, v1, s[10:11] sc1
	v_readlane_b32 s10, v249, 54
	v_readlane_b32 s11, v249, 55
	s_nop 0
	s_nop 0
	s_nop 2
	global_load_dword v7, v1, s[10:11] sc1
	v_readlane_b32 s10, v249, 56
	v_readlane_b32 s11, v249, 57
	s_nop 0
	s_nop 0
	s_nop 2
	global_load_dword v8, v1, s[10:11] sc1
	v_readlane_b32 s10, v249, 58
	v_readlane_b32 s11, v249, 59
	s_nop 0
	s_nop 0
	s_nop 2
	global_load_dword v9, v1, s[10:11] sc1
	v_readlane_b32 s10, v249, 60
	v_readlane_b32 s11, v249, 61
	s_nop 0
	s_nop 0
	s_nop 2
	global_load_dword v10, v1, s[10:11] sc1
	v_readlane_b32 s10, v249, 62
	v_readlane_b32 s11, v249, 63
	s_nop 0
	s_nop 0
	s_nop 2
	global_load_dword v11, v1, s[10:11] sc1
	v_readlane_b32 s10, v248, 0
	v_readlane_b32 s11, v248, 1
	s_nop 0
	s_nop 0
	s_nop 2
	global_load_dword v12, v1, s[10:11] sc1
	v_readlane_b32 s10, v248, 2
	v_readlane_b32 s11, v248, 3
	s_nop 0
	s_nop 0
	s_nop 2
	global_load_dword v13, v1, s[10:11] sc1
	v_readlane_b32 s10, v248, 4
	v_readlane_b32 s11, v248, 5
	s_nop 0
	s_nop 0
	s_nop 2
	global_load_dword v14, v1, s[10:11] sc1
	v_readlane_b32 s10, v248, 6
	v_readlane_b32 s11, v248, 7
	s_nop 0
	s_nop 0
	s_nop 2
	global_load_dword v15, v1, s[10:11] sc1
	v_readlane_b32 s10, v248, 8
	v_readlane_b32 s11, v248, 9
	s_nop 0
	s_nop 0
	s_nop 2
	global_load_dword v16, v1, s[10:11] sc1
	s_mov_b64 s[10:11], -1
	s_nop 0
	s_nop 0
	s_waitcnt vmcnt(0)
	v_add_u32_e32 v17, v2, v0
	v_add_u32_e32 v17, v17, v3
	v_add_u32_e32 v17, v17, v4
	v_add_u32_e32 v17, v17, v5
	v_add_u32_e32 v17, v17, v6
	v_add_u32_e32 v17, v17, v7
	v_add_u32_e32 v17, v17, v8
	v_add_u32_e32 v17, v17, v9
	v_add_u32_e32 v17, v17, v10
	v_add_u32_e32 v17, v17, v11
	v_add_u32_e32 v17, v17, v12
	v_add_u32_e32 v17, v17, v13
	v_add_u32_e32 v17, v17, v14
	v_add_u32_e32 v17, v17, v15
	v_add_u32_e32 v17, v17, v16
	v_cmp_eq_u32_e32 vcc, s5, v17
	s_cbranch_vccnz .LBB0_452
	s_and_b32 s5, s4, 0xff
	s_cmp_eq_u32 s5, 0
	s_mov_b64 s[14:15], -1
	s_sleep 1
	s_cbranch_scc1 .LBB0_457
	s_and_b64 vcc, exec, s[14:15]
	s_cbranch_vccz .LBB0_452
